# v38 + P6 rows interleaved per workgroup: 32 rows of [0,8192) + 32 of [8192,16384) + 16 of the split-K tail instead of 80 contiguous rows
# baseline (speedup 1.0000x reference)
.LBB0_664:
	s_cmp_lt_i32 s76, 7
	s_cselect_b64 s[0:1], -1, 0
	s_cmp_gt_i32 s77, 6
	s_cselect_b64 s[2:3], -1, 0
	s_and_b64 s[0:1], s[0:1], s[2:3]
	s_andn2_b64 vcc, exec, s[0:1]
	s_cbranch_vccnz .LBB0_729
	s_abs_i32 s0, s33
	v_cvt_f32_u32_e32 v1, s0
	s_sub_i32 s3, 0, s0
	s_add_i32 s1, s33, 0x4fff
	s_xor_b32 s2, s1, s33
	v_rcp_iflag_f32_e32 v1, v1
	s_abs_i32 s1, s1
	s_ashr_i32 s2, s2, 31
	v_mbcnt_lo_u32_b32 v130, -1, 0
	v_mbcnt_hi_u32_b32 v130, -1, v130
	v_mul_f32_e32 v1, 0x4f7ffffe, v1
	v_cvt_u32_f32_e32 v1, v1
	s_nop 0
	v_readfirstlane_b32 s4, v1
	s_mul_i32 s3, s3, s4
	s_mul_hi_u32 s3, s4, s3
	s_add_i32 s4, s4, s3
	s_mul_hi_u32 s3, s1, s4
	s_mul_i32 s4, s3, s0
	s_sub_i32 s1, s1, s4
	s_add_i32 s5, s3, 1
	s_sub_i32 s4, s1, s0
	s_cmp_ge_u32 s1, s0
	s_cselect_b32 s3, s5, s3
	s_cselect_b32 s1, s4, s1
	s_add_i32 s4, s3, 1
	s_cmp_ge_u32 s1, s0
	s_cselect_b32 s0, s4, s3
	s_xor_b32 s0, s0, s2
	s_sub_i32 s1, s0, s2
	s_mul_i32 s0, s1, s92
	s_add_i32 s1, s0, s1
	s_min_i32 s7, s1, 0x5000
	s_mov_b32 s26, 3
	s_cmpk_lg_i32 s33, 0x100
	s_cbranch_scc1 .Lp6_rng_done
	s_mov_b32 s26, 0
	s_lshl_b32 s0, s92, 5
	s_add_i32 s7, s0, 32
.Lp6_rng_done:
	s_cmp_ge_i32 s0, s7
	s_mov_b32 s1, 0
	s_cbranch_scc1 .LBB0_675
	v_readlane_b32 s36, v254, 0
	v_lshlrev_b32_e32 v2, 2, v0
	s_waitcnt vmcnt(0)
	v_mov_b32_e32 v133, 0
	v_lshlrev_b32_e32 v132, 4, v0
	v_readlane_b32 s50, v254, 14
	v_readlane_b32 s51, v254, 15
	s_mov_b64 s[4:5], 0x2000
	v_add_u32_e32 v1, 0, v132
	v_lshl_add_u64 v[4:5], s[50:51], 0, v[132:133]
	v_ashrrev_i32_e32 v131, 31, v130
	v_lshlrev_b32_e32 v132, 2, v2
	v_mbcnt_lo_u32_b32 v2, -1, 0
	v_lshl_add_u64 v[134:135], v[4:5], 0, s[4:5]
	s_mov_b64 s[4:5], 0x4000
	v_lshlrev_b64 v[138:139], 3, v[130:131]
	v_mbcnt_hi_u32_b32 v186, -1, v2
	s_movk_i32 s2, 0x200
	s_add_u32 s16, s74, 0x100000
	v_lshl_add_u64 v[136:137], v[4:5], 0, s[4:5]
	v_lshl_add_u64 v[4:5], s[74:75], 0, v[138:139]
	s_mov_b64 s[8:9], 0x1d400000
	v_and_b32_e32 v2, 64, v186
	v_cmp_gt_u32_e64 s[2:3], s2, v0
	s_addc_u32 s17, s75, 0
	v_lshl_add_u32 v184, v130, 4, 0
	v_lshl_add_u64 v[140:141], v[4:5], 0, s[8:9]
	v_lshlrev_b64 v[142:143], 2, v[130:131]
	v_lshl_add_u64 v[144:145], s[72:73], 0, v[138:139]
	s_movk_i32 s18, 0x1000
	s_mov_b32 s19, 0x18400000
	v_mov_b32_e32 v185, 0x358637bd
	s_mov_b32 s20, 0x800000
	s_mov_b32 s6, 0x41000000
	s_mov_b32 s21, 0xc3e00000
	s_mov_b32 s22, 0x6c00000
	s_mov_b64 s[8:9], 0x10000
	s_mov_b64 s[10:11], 0x8000
	v_add_u32_e32 v187, 64, v2
	v_xor_b32_e32 v188, 1, v186
	v_xor_b32_e32 v189, 2, v186
	v_xor_b32_e32 v190, 4, v186
	v_xor_b32_e32 v191, 8, v186
	v_xor_b32_e32 v192, 16, v186
	v_xor_b32_e32 v193, 32, v186
	v_mov_b32_e32 v194, 0x43e00000
	v_readlane_b32 s37, v254, 1
	v_readlane_b32 s38, v254, 2
	v_readlane_b32 s39, v254, 3
	v_readlane_b32 s40, v254, 4
	v_readlane_b32 s41, v254, 5
	v_readlane_b32 s42, v254, 6
	v_readlane_b32 s43, v254, 7
	v_readlane_b32 s44, v254, 8
	v_readlane_b32 s45, v254, 9
	v_readlane_b32 s46, v254, 10
	v_readlane_b32 s47, v254, 11
	v_readlane_b32 s48, v254, 12
	v_readlane_b32 s49, v254, 13
	s_branch .LBB0_668

.Lp6_next_range:
	s_add_i32 s26, s26, 1
	s_cmp_eq_u32 s26, 1
	s_cbranch_scc0 .Lp6_nr2
	s_lshl_b32 s0, s92, 5
	s_add_i32 s0, s0, 0x2000
	s_add_i32 s7, s0, 32
	s_branch .LBB0_668
.Lp6_nr2:
	s_cmp_eq_u32 s26, 2
	s_cbranch_scc0 .LBB0_675
	s_lshl_b32 s0, s92, 4
	s_add_i32 s0, s0, 0x4000
	s_add_i32 s7, s0, 16
	s_branch .LBB0_668
